# P7 SwiGLU epilogue: 8 serial rowsq loads hoisted to epilogue top with counted waits; P1 stores sc0 sc1
# speedup vs baseline: 1.0041x; 1.0041x over previous
; __device__ __forceinline__ unsigned cvt_pk_bf16(float lo, float hi) { unsigned r; asm volatile("v_cvt_pk_bf16_f32 %0, %1, %2" : "=v"(r) : "v"(lo), "v"(hi)); return r; }
; __device__ __forceinline__ float siluf_(float x) { return x * __builtin_amdgcn_rcpf(1.f + __expf(-x)); }
;     __device__ __forceinline__ void operator()(const f32x4 (&acc)[2][2][4][2], const Unit& u, int wr, int wc, int fr, int fq) const {
;         const int row0 = u.pm * BM + wr * 64 + fr; const int col = u.pn * HALF + wc * 32 + 8 * fq;
; #pragma unroll
;         for (int ai = 0; ai < 2; ++ai)
; #pragma unroll
;             for (int m = 0; m < 4; ++m) { const size_t row = (size_t)(row0 + ai * HALF + m * 16);
;                 const float rstd = rsqrtf(rowsq[row] * (1.f / 2048.f) + RMS_EPS);
;                 float r[8];
; #pragma unroll
;                 for (int n = 0; n < 2; ++n)
; #pragma unroll
;                     for (int e = 0; e < 4; ++e) { const float g = acc[ai][0][m][n][e] * rstd, up = acc[ai][1][m][n][e] * rstd; r[n * 4 + e] = siluf_(g) * up; }
;                 u32x4 w; w.x = cvt_pk_bf16(r[0], r[1]); w.y = cvt_pk_bf16(r[2], r[3]); w.z = cvt_pk_bf16(r[4], r[5]); w.w = cvt_pk_bf16(r[6], r[7]);
;                 *(u32x4*)(hid + row * DFF + col) = w; }
.LBB0_708:
	v_lshl_add_u32 v144, s4, 8, v148
	v_ashrrev_i32_e32 v145, 31, v144
	v_lshl_add_u64 v[146:147], v[144:145], 2, s[10:11]
	global_load_dword v145, v[146:147], off
	global_load_dword v228, v[146:147], off offset:64
	global_load_dword v229, v[146:147], off offset:128
	global_load_dword v230, v[146:147], off offset:192
	global_load_dword v231, v[146:147], off offset:512
	global_load_dword v232, v[146:147], off offset:576
	global_load_dword v233, v[146:147], off offset:640
	global_load_dword v234, v[146:147], off offset:704
	v_lshl_or_b32 v156, s5, 7, v150
	v_mov_b32_e32 v161, v114
	v_mov_b32_e32 v114, v123
	v_mov_b32_e32 v158, v124
	v_mov_b32_e32 v159, v116
	v_mov_b32_e32 v116, v125
	v_mov_b32_e32 v124, v126
	v_mov_b32_e32 v125, v118
	v_mov_b32_e32 v118, v127
	v_mov_b32_e32 v126, v120
	v_mov_b32_e32 v127, v112
	v_mov_b32_e32 v112, v121
	v_mov_b32_e32 v160, v122
	v_mov_b64_e32 v[120:121], s[12:13]
	v_ashrrev_i32_e32 v157, 31, v156
	v_or_b32_e32 v164, 16, v144
	v_mad_i64_i32 v[162:163], s[4:5], v144, s57, v[120:121]
	v_lshlrev_b64 v[122:123], 1, v[156:157]
	v_ashrrev_i32_e32 v165, 31, v164
	v_lshl_add_u64 v[156:157], v[162:163], 0, v[122:123]
	v_lshl_add_u64 v[162:163], v[164:165], 2, s[10:11]
	s_waitcnt vmcnt(7)
	v_fmamk_f32 v145, v145, 0x3a000000, v154
	v_mul_f32_e32 v155, 0x4b800000, v145
	v_cmp_gt_f32_e32 vcc, s56, v145
	s_nop 1
	v_cndmask_b32_e32 v145, v145, v155, vcc
	v_rsq_f32_e32 v145, v145
	s_nop 0
	v_mul_f32_e32 v155, 0x45800000, v145
	v_cndmask_b32_e32 v166, v145, v155, vcc
	v_pk_mul_f32 v[114:115], v[114:115], v[166:167] op_sel_hi:[1,0]
	v_pk_mul_f32 v[158:159], v[158:159], v[166:167] op_sel_hi:[1,0]
	v_pk_mul_f32 v[116:117], v[116:117], v[166:167] op_sel_hi:[1,0]
	v_pk_mul_f32 v[124:125], v[124:125], v[166:167] op_sel_hi:[1,0]
	v_pk_mul_f32 v[118:119], v[118:119], v[166:167] op_sel_hi:[1,0]
	v_pk_mul_f32 v[126:127], v[126:127], v[166:167] op_sel_hi:[1,0]
	v_pk_mul_f32 v[112:113], v[112:113], v[166:167] op_sel_hi:[1,0]
	v_pk_mul_f32 v[160:161], v[160:161], v[166:167] op_sel_hi:[1,0]
	v_mul_f32_e32 v170, 0xbfb8aa3b, v115
	v_mul_f32_e32 v145, 0xbfb8aa3b, v159
	v_mul_f32_e32 v155, 0xbfb8aa3b, v117
	v_mul_f32_e32 v165, 0xbfb8aa3b, v125
	v_mul_f32_e32 v166, 0xbfb8aa3b, v119
	v_mul_f32_e32 v167, 0xbfb8aa3b, v127
	v_mul_f32_e32 v168, 0xbfb8aa3b, v113
	v_mul_f32_e32 v169, 0xbfb8aa3b, v161
	v_exp_f32_e32 v170, v170
	v_exp_f32_e32 v145, v145
	v_exp_f32_e32 v155, v155
	v_exp_f32_e32 v165, v165
	v_exp_f32_e32 v166, v166
	v_exp_f32_e32 v167, v167
	v_exp_f32_e32 v168, v168
	v_exp_f32_e32 v169, v169
	v_add_f32_e32 v170, 1.0, v170
	v_add_f32_e32 v145, 1.0, v145
	v_add_f32_e32 v155, 1.0, v155
	v_add_f32_e32 v165, 1.0, v165
	v_add_f32_e32 v166, 1.0, v166
	v_add_f32_e32 v167, 1.0, v167
	v_add_f32_e32 v168, 1.0, v168
	v_add_f32_e32 v169, 1.0, v169
	v_rcp_f32_e32 v170, v170
	v_rcp_f32_e32 v145, v145
	v_rcp_f32_e32 v155, v155
	v_rcp_f32_e32 v165, v165
	v_rcp_f32_e32 v166, v166
	v_rcp_f32_e32 v167, v167
	v_rcp_f32_e32 v168, v168
	v_rcp_f32_e32 v169, v169
	v_mul_f32_e32 v115, v115, v170
	v_mul_f32_e32 v145, v159, v145
	v_mul_f32_e32 v117, v117, v155
	v_mul_f32_e32 v125, v125, v165
	v_mul_f32_e32 v119, v119, v166
	v_mul_f32_e32 v127, v127, v167
	v_mul_f32_e32 v113, v113, v168
	v_mul_f32_e32 v155, v161, v169
	v_mul_f32_e32 v115, v114, v115
	v_mul_f32_e32 v145, v158, v145
	v_mul_f32_e32 v116, v116, v117
	v_mul_f32_e32 v117, v124, v125
	v_mul_f32_e32 v118, v118, v119
	v_mul_f32_e32 v119, v126, v127
	v_mul_f32_e32 v124, v112, v113
	v_mul_f32_e32 v125, v160, v155
	v_cvt_pk_bf16_f32 v112, v145, v116
	v_cvt_pk_bf16_f32 v113, v117, v118
	v_cvt_pk_bf16_f32 v114, v119, v124
	v_cvt_pk_bf16_f32 v115, v125, v115
	global_store_dwordx4 v[156:157], v[112:115], off
	s_nop 0
	s_nop 0
	v_mov_b32_e32 v113, v100
	v_mov_b32_e32 v100, v109
	v_mov_b32_e32 v109, v102
	v_mov_b32_e32 v102, v111
	v_mov_b32_e32 v111, v96
	v_mov_b32_e32 v96, v105
	v_mov_b32_e32 v105, v98
	v_mov_b32_e32 v98, v107
	v_mov_b32_e32 v112, v108
	v_mov_b32_e32 v108, v110
	v_mov_b32_e32 v110, v104
	v_mov_b32_e32 v104, v106
	v_or_b32_e32 v106, 32, v144
	v_mad_i64_i32 v[114:115], s[4:5], v164, s57, v[120:121]
	v_lshl_add_u64 v[114:115], v[114:115], 0, v[122:123]
	s_waitcnt vmcnt(7)
	v_fmamk_f32 v107, v228, 0x3a000000, v154
	v_mul_f32_e32 v116, 0x4b800000, v107
	v_cmp_gt_f32_e32 vcc, s56, v107
	s_nop 1
	v_cndmask_b32_e32 v107, v107, v116, vcc
	v_rsq_f32_e32 v118, v107
	v_ashrrev_i32_e32 v107, 31, v106
	v_lshl_add_u64 v[116:117], v[106:107], 2, s[10:11]
	v_mul_f32_e32 v107, 0x45800000, v118
	v_cndmask_b32_e32 v118, v118, v107, vcc
	v_pk_mul_f32 v[98:99], v[98:99], v[118:119] op_sel_hi:[1,0]
	v_pk_mul_f32 v[112:113], v[112:113], v[118:119] op_sel_hi:[1,0]
	v_pk_mul_f32 v[100:101], v[100:101], v[118:119] op_sel_hi:[1,0]
	v_pk_mul_f32 v[108:109], v[108:109], v[118:119] op_sel_hi:[1,0]
	v_pk_mul_f32 v[102:103], v[102:103], v[118:119] op_sel_hi:[1,0]
	v_pk_mul_f32 v[110:111], v[110:111], v[118:119] op_sel_hi:[1,0]
	v_pk_mul_f32 v[96:97], v[96:97], v[118:119] op_sel_hi:[1,0]
	v_pk_mul_f32 v[104:105], v[104:105], v[118:119] op_sel_hi:[1,0]
	v_mul_f32_e32 v145, 0xbfb8aa3b, v99
	v_mul_f32_e32 v107, 0xbfb8aa3b, v113
	v_mul_f32_e32 v118, 0xbfb8aa3b, v101
	v_mul_f32_e32 v119, 0xbfb8aa3b, v109
	v_mul_f32_e32 v124, 0xbfb8aa3b, v103
	v_mul_f32_e32 v125, 0xbfb8aa3b, v111
	v_mul_f32_e32 v126, 0xbfb8aa3b, v97
	v_mul_f32_e32 v127, 0xbfb8aa3b, v105
	v_exp_f32_e32 v145, v145
	v_exp_f32_e32 v107, v107
	v_exp_f32_e32 v118, v118
	v_exp_f32_e32 v119, v119
	v_exp_f32_e32 v124, v124
	v_exp_f32_e32 v125, v125
	v_exp_f32_e32 v126, v126
	v_exp_f32_e32 v127, v127
	v_add_f32_e32 v145, 1.0, v145
	v_add_f32_e32 v107, 1.0, v107
; __device__ __forceinline__ unsigned cvt_pk_bf16(float lo, float hi) { unsigned r; asm volatile("v_cvt_pk_bf16_f32 %0, %1, %2" : "=v"(r) : "v"(lo), "v"(hi)); return r; }
; __device__ __forceinline__ float siluf_(float x) { return x * __builtin_amdgcn_rcpf(1.f + __expf(-x)); }
;     __device__ __forceinline__ void operator()(const f32x4 (&acc)[2][2][4][2], const Unit& u, int wr, int wc, int fr, int fq) const {
;         const int row0 = u.pm * BM + wr * 64 + fr; const int col = u.pn * HALF + wc * 32 + 8 * fq;
; #pragma unroll
;         for (int ai = 0; ai < 2; ++ai)
; #pragma unroll
;             for (int m = 0; m < 4; ++m) { const size_t row = (size_t)(row0 + ai * HALF + m * 16);
;                 const float rstd = rsqrtf(rowsq[row] * (1.f / 2048.f) + RMS_EPS);
;                 float r[8];
; #pragma unroll
;                 for (int n = 0; n < 2; ++n)
; #pragma unroll
;                     for (int e = 0; e < 4; ++e) { const float g = acc[ai][0][m][n][e] * rstd, up = acc[ai][1][m][n][e] * rstd; r[n * 4 + e] = siluf_(g) * up; }
;                 u32x4 w; w.x = cvt_pk_bf16(r[0], r[1]); w.y = cvt_pk_bf16(r[2], r[3]); w.z = cvt_pk_bf16(r[4], r[5]); w.w = cvt_pk_bf16(r[6], r[7]);
;                 *(u32x4*)(hid + row * DFF + col) = w; }
	v_add_f32_e32 v118, 1.0, v118
	v_add_f32_e32 v119, 1.0, v119
	v_add_f32_e32 v124, 1.0, v124
	v_add_f32_e32 v125, 1.0, v125
	v_add_f32_e32 v126, 1.0, v126
	v_add_f32_e32 v127, 1.0, v127
	v_rcp_f32_e32 v145, v145
	v_rcp_f32_e32 v107, v107
	v_rcp_f32_e32 v118, v118
	v_rcp_f32_e32 v119, v119
	v_rcp_f32_e32 v124, v124
	v_rcp_f32_e32 v125, v125
	v_rcp_f32_e32 v126, v126
	v_rcp_f32_e32 v127, v127
	v_mul_f32_e32 v99, v99, v145
	v_mul_f32_e32 v107, v113, v107
	v_mul_f32_e32 v101, v101, v118
	v_mul_f32_e32 v109, v109, v119
	v_mul_f32_e32 v103, v103, v124
	v_mul_f32_e32 v111, v111, v125
	v_mul_f32_e32 v97, v97, v126
	v_mul_f32_e32 v105, v105, v127
	v_mul_f32_e32 v99, v98, v99
	v_mul_f32_e32 v107, v112, v107
	v_mul_f32_e32 v100, v100, v101
	v_mul_f32_e32 v101, v108, v109
	v_mul_f32_e32 v102, v102, v103
	v_mul_f32_e32 v103, v110, v111
	v_mul_f32_e32 v108, v96, v97
	v_mul_f32_e32 v104, v104, v105
	v_cvt_pk_bf16_f32 v96, v107, v100
	v_cvt_pk_bf16_f32 v97, v101, v102
	v_cvt_pk_bf16_f32 v98, v103, v108
	v_cvt_pk_bf16_f32 v99, v104, v99
	global_store_dwordx4 v[114:115], v[96:99], off
	s_nop 0
	s_nop 0
	v_mov_b32_e32 v97, v84
	v_mov_b32_e32 v84, v93
	v_mov_b32_e32 v93, v86
	v_mov_b32_e32 v86, v95
	v_mov_b32_e32 v95, v80
	v_mov_b32_e32 v80, v89
	v_mov_b32_e32 v89, v82
	v_mov_b32_e32 v82, v91
	v_mov_b32_e32 v96, v92
	v_mov_b32_e32 v92, v94
	v_mov_b32_e32 v94, v88
	v_mov_b32_e32 v88, v90
	v_or_b32_e32 v90, 48, v144
	v_mad_i64_i32 v[98:99], s[4:5], v106, s57, v[120:121]
	v_lshl_add_u64 v[98:99], v[98:99], 0, v[122:123]
	s_waitcnt vmcnt(7)
	v_fmamk_f32 v91, v229, 0x3a000000, v154
	v_mul_f32_e32 v100, 0x4b800000, v91
	v_cmp_gt_f32_e32 vcc, s56, v91
	s_nop 1
	v_cndmask_b32_e32 v91, v91, v100, vcc
	v_rsq_f32_e32 v102, v91
	v_ashrrev_i32_e32 v91, 31, v90
	v_lshl_add_u64 v[100:101], v[90:91], 2, s[10:11]
	v_mul_f32_e32 v91, 0x45800000, v102
	v_cndmask_b32_e32 v102, v102, v91, vcc
	v_pk_mul_f32 v[82:83], v[82:83], v[102:103] op_sel_hi:[1,0]
	v_pk_mul_f32 v[96:97], v[96:97], v[102:103] op_sel_hi:[1,0]
	v_pk_mul_f32 v[84:85], v[84:85], v[102:103] op_sel_hi:[1,0]
	v_pk_mul_f32 v[92:93], v[92:93], v[102:103] op_sel_hi:[1,0]
	v_pk_mul_f32 v[86:87], v[86:87], v[102:103] op_sel_hi:[1,0]
	v_pk_mul_f32 v[94:95], v[94:95], v[102:103] op_sel_hi:[1,0]
	v_pk_mul_f32 v[80:81], v[80:81], v[102:103] op_sel_hi:[1,0]
	v_pk_mul_f32 v[88:89], v[88:89], v[102:103] op_sel_hi:[1,0]
	v_mul_f32_e32 v108, 0xbfb8aa3b, v83
	v_mul_f32_e32 v91, 0xbfb8aa3b, v97
	v_mul_f32_e32 v102, 0xbfb8aa3b, v85
	v_mul_f32_e32 v103, 0xbfb8aa3b, v93
	v_mul_f32_e32 v104, 0xbfb8aa3b, v87
	v_mul_f32_e32 v105, 0xbfb8aa3b, v95
	v_mul_f32_e32 v106, 0xbfb8aa3b, v81
	v_mul_f32_e32 v107, 0xbfb8aa3b, v89
	v_exp_f32_e32 v108, v108
	v_exp_f32_e32 v91, v91
	v_exp_f32_e32 v102, v102
	v_exp_f32_e32 v103, v103
	v_exp_f32_e32 v104, v104
	v_exp_f32_e32 v105, v105
	v_exp_f32_e32 v106, v106
	v_exp_f32_e32 v107, v107
	v_add_f32_e32 v108, 1.0, v108
	v_add_f32_e32 v91, 1.0, v91
	v_add_f32_e32 v102, 1.0, v102
	v_add_f32_e32 v103, 1.0, v103
	v_add_f32_e32 v104, 1.0, v104
	v_add_f32_e32 v105, 1.0, v105
	v_add_f32_e32 v106, 1.0, v106
	v_add_f32_e32 v107, 1.0, v107
	v_rcp_f32_e32 v108, v108
	v_rcp_f32_e32 v91, v91
	v_rcp_f32_e32 v102, v102
	v_rcp_f32_e32 v103, v103
	v_rcp_f32_e32 v104, v104
	v_rcp_f32_e32 v105, v105
	v_rcp_f32_e32 v106, v106
	v_rcp_f32_e32 v107, v107
	v_mul_f32_e32 v83, v83, v108
	v_mul_f32_e32 v91, v97, v91
	v_mul_f32_e32 v85, v85, v102
	v_mul_f32_e32 v93, v93, v103
	v_mul_f32_e32 v87, v87, v104
	v_mul_f32_e32 v95, v95, v105
	v_mul_f32_e32 v81, v81, v106
	v_mul_f32_e32 v89, v89, v107
	v_mul_f32_e32 v83, v82, v83
	v_mul_f32_e32 v91, v96, v91
	v_mul_f32_e32 v84, v84, v85
	v_mul_f32_e32 v85, v92, v93
	v_mul_f32_e32 v86, v86, v87
	v_mul_f32_e32 v87, v94, v95
	v_mul_f32_e32 v92, v80, v81
	v_mul_f32_e32 v88, v88, v89
	v_cvt_pk_bf16_f32 v80, v91, v84
	v_cvt_pk_bf16_f32 v81, v85, v86
	v_cvt_pk_bf16_f32 v82, v87, v92
	v_cvt_pk_bf16_f32 v83, v88, v83
	global_store_dwordx4 v[98:99], v[80:83], off
	s_nop 0
	s_nop 0
	v_mov_b32_e32 v80, v76
	v_mov_b32_e32 v76, v78
	v_mov_b32_e32 v78, v68
	v_mov_b32_e32 v68, v70
	v_mov_b32_e32 v81, v72
	v_mov_b32_e32 v72, v77
	v_mov_b32_e32 v77, v74
	v_mov_b32_e32 v74, v79
	v_mov_b32_e32 v79, v64
	v_mov_b32_e32 v64, v69
	v_mov_b32_e32 v69, v66
	v_mov_b32_e32 v66, v71
	s_waitcnt vmcnt(7)
; __device__ __forceinline__ unsigned cvt_pk_bf16(float lo, float hi) { unsigned r; asm volatile("v_cvt_pk_bf16_f32 %0, %1, %2" : "=v"(r) : "v"(lo), "v"(hi)); return r; }
; __device__ __forceinline__ float siluf_(float x) { return x * __builtin_amdgcn_rcpf(1.f + __expf(-x)); }
;     __device__ __forceinline__ void operator()(const f32x4 (&acc)[2][2][4][2], const Unit& u, int wr, int wc, int fr, int fq) const {
;         const int row0 = u.pm * BM + wr * 64 + fr; const int col = u.pn * HALF + wc * 32 + 8 * fq;
; #pragma unroll
;         for (int ai = 0; ai < 2; ++ai)
; #pragma unroll
;             for (int m = 0; m < 4; ++m) { const size_t row = (size_t)(row0 + ai * HALF + m * 16);
;                 const float rstd = rsqrtf(rowsq[row] * (1.f / 2048.f) + RMS_EPS);
;                 float r[8];
; #pragma unroll
;                 for (int n = 0; n < 2; ++n)
; #pragma unroll
;                     for (int e = 0; e < 4; ++e) { const float g = acc[ai][0][m][n][e] * rstd, up = acc[ai][1][m][n][e] * rstd; r[n * 4 + e] = siluf_(g) * up; }
;                 u32x4 w; w.x = cvt_pk_bf16(r[0], r[1]); w.y = cvt_pk_bf16(r[2], r[3]); w.z = cvt_pk_bf16(r[4], r[5]); w.w = cvt_pk_bf16(r[6], r[7]);
;                 *(u32x4*)(hid + row * DFF + col) = w; }
	v_fmamk_f32 v70, v230, 0x3a000000, v154
	v_mul_f32_e32 v71, 0x4b800000, v70
	v_cmp_gt_f32_e32 vcc, s56, v70
	s_nop 1
	v_cndmask_b32_e32 v70, v70, v71, vcc
	v_rsq_f32_e32 v82, v70
	v_mad_i64_i32 v[70:71], s[4:5], v90, s57, v[120:121]
	v_lshl_add_u64 v[70:71], v[70:71], 0, v[122:123]
	v_mul_f32_e32 v83, 0x45800000, v82
	v_cndmask_b32_e32 v82, v82, v83, vcc
	v_pk_mul_f32 v[66:67], v[66:67], v[82:83] op_sel_hi:[1,0]
	v_pk_mul_f32 v[80:81], v[80:81], v[82:83] op_sel_hi:[1,0]
	v_pk_mul_f32 v[72:73], v[72:73], v[82:83] op_sel_hi:[1,0]
	v_pk_mul_f32 v[76:77], v[76:77], v[82:83] op_sel_hi:[1,0]
	v_pk_mul_f32 v[74:75], v[74:75], v[82:83] op_sel_hi:[1,0]
	v_pk_mul_f32 v[78:79], v[78:79], v[82:83] op_sel_hi:[1,0]
	v_pk_mul_f32 v[64:65], v[64:65], v[82:83] op_sel_hi:[1,0]
	v_pk_mul_f32 v[68:69], v[68:69], v[82:83] op_sel_hi:[1,0]
	v_mul_f32_e32 v89, 0xbfb8aa3b, v67
	v_mul_f32_e32 v82, 0xbfb8aa3b, v81
	v_mul_f32_e32 v83, 0xbfb8aa3b, v73
	v_mul_f32_e32 v84, 0xbfb8aa3b, v77
	v_mul_f32_e32 v85, 0xbfb8aa3b, v75
	v_mul_f32_e32 v86, 0xbfb8aa3b, v79
	v_mul_f32_e32 v87, 0xbfb8aa3b, v65
	v_mul_f32_e32 v88, 0xbfb8aa3b, v69
	v_exp_f32_e32 v89, v89
	v_exp_f32_e32 v82, v82
	v_exp_f32_e32 v83, v83
	v_exp_f32_e32 v84, v84
	v_exp_f32_e32 v85, v85
	v_exp_f32_e32 v86, v86
	v_exp_f32_e32 v87, v87
	v_exp_f32_e32 v88, v88
	v_add_f32_e32 v89, 1.0, v89
	v_add_f32_e32 v82, 1.0, v82
	v_add_f32_e32 v83, 1.0, v83
	v_add_f32_e32 v84, 1.0, v84
	v_add_f32_e32 v85, 1.0, v85
	v_add_f32_e32 v86, 1.0, v86
	v_add_f32_e32 v87, 1.0, v87
	v_add_f32_e32 v88, 1.0, v88
	v_rcp_f32_e32 v89, v89
	v_rcp_f32_e32 v82, v82
	v_rcp_f32_e32 v83, v83
	v_rcp_f32_e32 v84, v84
	v_rcp_f32_e32 v85, v85
	v_rcp_f32_e32 v86, v86
	v_rcp_f32_e32 v87, v87
	v_rcp_f32_e32 v88, v88
	v_mul_f32_e32 v67, v67, v89
	v_mul_f32_e32 v81, v81, v82
	v_mul_f32_e32 v73, v73, v83
	v_mul_f32_e32 v77, v77, v84
	v_mul_f32_e32 v75, v75, v85
	v_mul_f32_e32 v79, v79, v86
	v_mul_f32_e32 v65, v65, v87
	v_mul_f32_e32 v69, v69, v88
	v_mul_f32_e32 v67, v66, v67
	v_mul_f32_e32 v80, v80, v81
	v_mul_f32_e32 v72, v72, v73
	v_mul_f32_e32 v73, v76, v77
	v_mul_f32_e32 v74, v74, v75
	v_mul_f32_e32 v75, v78, v79
	v_mul_f32_e32 v76, v64, v65
	v_mul_f32_e32 v68, v68, v69
	v_cvt_pk_bf16_f32 v64, v80, v72
	v_cvt_pk_bf16_f32 v65, v73, v74
	v_cvt_pk_bf16_f32 v66, v75, v76
	v_cvt_pk_bf16_f32 v67, v68, v67
	global_store_dwordx4 v[70:71], v[64:67], off
	s_nop 0
	s_nop 0
	v_mov_b32_e32 v65, v56
	v_mov_b32_e32 v56, v61
	v_mov_b32_e32 v61, v58
	v_mov_b32_e32 v58, v63
	v_mov_b32_e32 v63, v48
	v_mov_b32_e32 v48, v53
	v_mov_b32_e32 v53, v50
	v_mov_b32_e32 v50, v55
	v_mov_b32_e32 v64, v60
	v_mov_b32_e32 v60, v62
	v_mov_b32_e32 v62, v52
	v_mov_b32_e32 v52, v54
	v_add_u32_e32 v54, 0x80, v144
	s_waitcnt vmcnt(7)
	v_fmamk_f32 v55, v231, 0x3a000000, v154
	v_mul_f32_e32 v66, 0x4b800000, v55
	v_cmp_gt_f32_e32 vcc, s56, v55
	s_nop 1
	v_cndmask_b32_e32 v55, v55, v66, vcc
	v_rsq_f32_e32 v66, v55
	v_mad_i64_i32 v[54:55], s[4:5], v54, s57, v[120:121]
	v_lshl_add_u64 v[54:55], v[54:55], 0, v[122:123]
	v_mul_f32_e32 v67, 0x45800000, v66
	v_cndmask_b32_e32 v66, v66, v67, vcc
	v_pk_mul_f32 v[50:51], v[50:51], v[66:67] op_sel_hi:[1,0]
	v_pk_mul_f32 v[64:65], v[64:65], v[66:67] op_sel_hi:[1,0]
	v_pk_mul_f32 v[56:57], v[56:57], v[66:67] op_sel_hi:[1,0]
	v_pk_mul_f32 v[60:61], v[60:61], v[66:67] op_sel_hi:[1,0]
	v_pk_mul_f32 v[58:59], v[58:59], v[66:67] op_sel_hi:[1,0]
	v_pk_mul_f32 v[62:63], v[62:63], v[66:67] op_sel_hi:[1,0]
	v_pk_mul_f32 v[48:49], v[48:49], v[66:67] op_sel_hi:[1,0]
	v_pk_mul_f32 v[52:53], v[52:53], v[66:67] op_sel_hi:[1,0]
	v_mul_f32_e32 v73, 0xbfb8aa3b, v51
	v_mul_f32_e32 v66, 0xbfb8aa3b, v65
	v_mul_f32_e32 v67, 0xbfb8aa3b, v57
	v_mul_f32_e32 v68, 0xbfb8aa3b, v61
	v_mul_f32_e32 v69, 0xbfb8aa3b, v59
	v_mul_f32_e32 v70, 0xbfb8aa3b, v63
	v_mul_f32_e32 v71, 0xbfb8aa3b, v49
	v_mul_f32_e32 v72, 0xbfb8aa3b, v53
	v_exp_f32_e32 v73, v73
	v_exp_f32_e32 v66, v66
	v_exp_f32_e32 v67, v67
	v_exp_f32_e32 v68, v68
	v_exp_f32_e32 v69, v69
	v_exp_f32_e32 v70, v70
	v_exp_f32_e32 v71, v71
	v_exp_f32_e32 v72, v72
	v_add_f32_e32 v73, 1.0, v73
	v_add_f32_e32 v66, 1.0, v66
	v_add_f32_e32 v67, 1.0, v67
	v_add_f32_e32 v68, 1.0, v68
	v_add_f32_e32 v69, 1.0, v69
	v_add_f32_e32 v70, 1.0, v70
	v_add_f32_e32 v71, 1.0, v71
	v_add_f32_e32 v72, 1.0, v72
	v_rcp_f32_e32 v73, v73
	v_rcp_f32_e32 v66, v66
	v_rcp_f32_e32 v67, v67
	v_rcp_f32_e32 v68, v68
	v_rcp_f32_e32 v69, v69
	v_rcp_f32_e32 v70, v70
	v_rcp_f32_e32 v71, v71
	v_rcp_f32_e32 v72, v72
	v_mul_f32_e32 v51, v51, v73
	v_mul_f32_e32 v65, v65, v66
	v_mul_f32_e32 v57, v57, v67
	v_mul_f32_e32 v61, v61, v68
	v_mul_f32_e32 v59, v59, v69
	v_mul_f32_e32 v63, v63, v70
	v_mul_f32_e32 v49, v49, v71
	v_mul_f32_e32 v53, v53, v72
	v_mul_f32_e32 v51, v50, v51
	v_mul_f32_e32 v64, v64, v65
	v_mul_f32_e32 v56, v56, v57
	v_mul_f32_e32 v57, v60, v61
	v_mul_f32_e32 v58, v58, v59
	v_mul_f32_e32 v59, v62, v63
	v_mul_f32_e32 v60, v48, v49
	v_mul_f32_e32 v52, v52, v53
	v_cvt_pk_bf16_f32 v48, v64, v56
	v_cvt_pk_bf16_f32 v49, v57, v58
	v_cvt_pk_bf16_f32 v50, v59, v60
	v_cvt_pk_bf16_f32 v51, v52, v51
	global_store_dwordx4 v[54:55], v[48:51], off
	s_nop 0
	s_nop 0
	v_mov_b32_e32 v49, v40
	v_mov_b32_e32 v40, v45
	v_mov_b32_e32 v45, v42
	v_mov_b32_e32 v42, v47
	v_mov_b32_e32 v47, v32
	v_mov_b32_e32 v32, v37
	v_mov_b32_e32 v37, v34
	v_mov_b32_e32 v34, v39
	v_mov_b32_e32 v48, v44
	v_mov_b32_e32 v44, v46
	v_mov_b32_e32 v46, v36
	v_mov_b32_e32 v36, v38
	v_add_u32_e32 v38, 0x90, v144
	s_waitcnt vmcnt(7)
; __device__ __forceinline__ unsigned cvt_pk_bf16(float lo, float hi) { unsigned r; asm volatile("v_cvt_pk_bf16_f32 %0, %1, %2" : "=v"(r) : "v"(lo), "v"(hi)); return r; }
; __device__ __forceinline__ float siluf_(float x) { return x * __builtin_amdgcn_rcpf(1.f + __expf(-x)); }
;     __device__ __forceinline__ void operator()(const f32x4 (&acc)[2][2][4][2], const Unit& u, int wr, int wc, int fr, int fq) const {
;         const int row0 = u.pm * BM + wr * 64 + fr; const int col = u.pn * HALF + wc * 32 + 8 * fq;
; #pragma unroll
;         for (int ai = 0; ai < 2; ++ai)
; #pragma unroll
;             for (int m = 0; m < 4; ++m) { const size_t row = (size_t)(row0 + ai * HALF + m * 16);
;                 const float rstd = rsqrtf(rowsq[row] * (1.f / 2048.f) + RMS_EPS);
;                 float r[8];
; #pragma unroll
;                 for (int n = 0; n < 2; ++n)
; #pragma unroll
;                     for (int e = 0; e < 4; ++e) { const float g = acc[ai][0][m][n][e] * rstd, up = acc[ai][1][m][n][e] * rstd; r[n * 4 + e] = siluf_(g) * up; }
;                 u32x4 w; w.x = cvt_pk_bf16(r[0], r[1]); w.y = cvt_pk_bf16(r[2], r[3]); w.z = cvt_pk_bf16(r[4], r[5]); w.w = cvt_pk_bf16(r[6], r[7]);
;                 *(u32x4*)(hid + row * DFF + col) = w; }
	v_fmamk_f32 v39, v232, 0x3a000000, v154
	v_mul_f32_e32 v50, 0x4b800000, v39
	v_cmp_gt_f32_e32 vcc, s56, v39
	s_nop 1
	v_cndmask_b32_e32 v39, v39, v50, vcc
	v_rsq_f32_e32 v50, v39
	v_mad_i64_i32 v[38:39], s[4:5], v38, s57, v[120:121]
	v_lshl_add_u64 v[38:39], v[38:39], 0, v[122:123]
	v_mul_f32_e32 v51, 0x45800000, v50
	v_cndmask_b32_e32 v50, v50, v51, vcc
	v_pk_mul_f32 v[34:35], v[34:35], v[50:51] op_sel_hi:[1,0]
	v_pk_mul_f32 v[48:49], v[48:49], v[50:51] op_sel_hi:[1,0]
	v_pk_mul_f32 v[40:41], v[40:41], v[50:51] op_sel_hi:[1,0]
	v_pk_mul_f32 v[44:45], v[44:45], v[50:51] op_sel_hi:[1,0]
	v_pk_mul_f32 v[42:43], v[42:43], v[50:51] op_sel_hi:[1,0]
	v_pk_mul_f32 v[46:47], v[46:47], v[50:51] op_sel_hi:[1,0]
	v_pk_mul_f32 v[32:33], v[32:33], v[50:51] op_sel_hi:[1,0]
	v_pk_mul_f32 v[36:37], v[36:37], v[50:51] op_sel_hi:[1,0]
	v_mul_f32_e32 v57, 0xbfb8aa3b, v35
	v_mul_f32_e32 v50, 0xbfb8aa3b, v49
	v_mul_f32_e32 v51, 0xbfb8aa3b, v41
	v_mul_f32_e32 v52, 0xbfb8aa3b, v45
	v_mul_f32_e32 v53, 0xbfb8aa3b, v43
	v_mul_f32_e32 v54, 0xbfb8aa3b, v47
	v_mul_f32_e32 v55, 0xbfb8aa3b, v33
	v_mul_f32_e32 v56, 0xbfb8aa3b, v37
	v_exp_f32_e32 v57, v57
	v_exp_f32_e32 v50, v50
	v_exp_f32_e32 v51, v51
	v_exp_f32_e32 v52, v52
	v_exp_f32_e32 v53, v53
	v_exp_f32_e32 v54, v54
	v_exp_f32_e32 v55, v55
	v_exp_f32_e32 v56, v56
	v_add_f32_e32 v57, 1.0, v57
	v_add_f32_e32 v50, 1.0, v50
	v_add_f32_e32 v51, 1.0, v51
	v_add_f32_e32 v52, 1.0, v52
	v_add_f32_e32 v53, 1.0, v53
	v_add_f32_e32 v54, 1.0, v54
	v_add_f32_e32 v55, 1.0, v55
	v_add_f32_e32 v56, 1.0, v56
	v_rcp_f32_e32 v57, v57
	v_rcp_f32_e32 v50, v50
	v_rcp_f32_e32 v51, v51
	v_rcp_f32_e32 v52, v52
	v_rcp_f32_e32 v53, v53
	v_rcp_f32_e32 v54, v54
	v_rcp_f32_e32 v55, v55
	v_rcp_f32_e32 v56, v56
	v_mul_f32_e32 v35, v35, v57
	v_mul_f32_e32 v49, v49, v50
	v_mul_f32_e32 v41, v41, v51
	v_mul_f32_e32 v45, v45, v52
	v_mul_f32_e32 v43, v43, v53
	v_mul_f32_e32 v47, v47, v54
	v_mul_f32_e32 v33, v33, v55
	v_mul_f32_e32 v37, v37, v56
	v_mul_f32_e32 v35, v34, v35
	v_mul_f32_e32 v48, v48, v49
	v_mul_f32_e32 v40, v40, v41
	v_mul_f32_e32 v41, v44, v45
	v_mul_f32_e32 v42, v42, v43
	v_mul_f32_e32 v43, v46, v47
	v_mul_f32_e32 v44, v32, v33
	v_mul_f32_e32 v36, v36, v37
	v_cvt_pk_bf16_f32 v32, v48, v40
	v_cvt_pk_bf16_f32 v33, v41, v42
	v_cvt_pk_bf16_f32 v34, v43, v44
	v_cvt_pk_bf16_f32 v35, v36, v35
	global_store_dwordx4 v[38:39], v[32:35], off
	s_nop 0
	s_nop 0
	v_mov_b32_e32 v33, v24
	v_mov_b32_e32 v24, v29
	v_mov_b32_e32 v29, v26
	v_mov_b32_e32 v26, v31
	v_mov_b32_e32 v31, v16
	v_mov_b32_e32 v16, v21
	v_mov_b32_e32 v21, v18
	v_mov_b32_e32 v18, v23
	v_mov_b32_e32 v32, v28
	v_mov_b32_e32 v28, v30
	v_mov_b32_e32 v30, v20
	v_mov_b32_e32 v20, v22
	v_add_u32_e32 v22, 0xa0, v144
	s_waitcnt vmcnt(7)
; __device__ __forceinline__ unsigned cvt_pk_bf16(float lo, float hi) { unsigned r; asm volatile("v_cvt_pk_bf16_f32 %0, %1, %2" : "=v"(r) : "v"(lo), "v"(hi)); return r; }
; __device__ __forceinline__ float siluf_(float x) { return x * __builtin_amdgcn_rcpf(1.f + __expf(-x)); }
;     __device__ __forceinline__ void operator()(const f32x4 (&acc)[2][2][4][2], const Unit& u, int wr, int wc, int fr, int fq) const {
;         const int row0 = u.pm * BM + wr * 64 + fr; const int col = u.pn * HALF + wc * 32 + 8 * fq;
; #pragma unroll
;         for (int ai = 0; ai < 2; ++ai)
; #pragma unroll
;             for (int m = 0; m < 4; ++m) { const size_t row = (size_t)(row0 + ai * HALF + m * 16);
;                 const float rstd = rsqrtf(rowsq[row] * (1.f / 2048.f) + RMS_EPS);
;                 float r[8];
; #pragma unroll
;                 for (int n = 0; n < 2; ++n)
; #pragma unroll
;                     for (int e = 0; e < 4; ++e) { const float g = acc[ai][0][m][n][e] * rstd, up = acc[ai][1][m][n][e] * rstd; r[n * 4 + e] = siluf_(g) * up; }
;                 u32x4 w; w.x = cvt_pk_bf16(r[0], r[1]); w.y = cvt_pk_bf16(r[2], r[3]); w.z = cvt_pk_bf16(r[4], r[5]); w.w = cvt_pk_bf16(r[6], r[7]);
;                 *(u32x4*)(hid + row * DFF + col) = w; }
	v_fmamk_f32 v23, v233, 0x3a000000, v154
	v_mul_f32_e32 v34, 0x4b800000, v23
	v_cmp_gt_f32_e32 vcc, s56, v23
	s_nop 1
	v_cndmask_b32_e32 v23, v23, v34, vcc
	v_rsq_f32_e32 v34, v23
	v_mad_i64_i32 v[22:23], s[4:5], v22, s57, v[120:121]
	v_lshl_add_u64 v[22:23], v[22:23], 0, v[122:123]
	v_mul_f32_e32 v35, 0x45800000, v34
	v_cndmask_b32_e32 v34, v34, v35, vcc
	v_pk_mul_f32 v[18:19], v[18:19], v[34:35] op_sel_hi:[1,0]
	v_pk_mul_f32 v[32:33], v[32:33], v[34:35] op_sel_hi:[1,0]
	v_pk_mul_f32 v[24:25], v[24:25], v[34:35] op_sel_hi:[1,0]
	v_pk_mul_f32 v[28:29], v[28:29], v[34:35] op_sel_hi:[1,0]
	v_pk_mul_f32 v[26:27], v[26:27], v[34:35] op_sel_hi:[1,0]
	v_pk_mul_f32 v[30:31], v[30:31], v[34:35] op_sel_hi:[1,0]
	v_pk_mul_f32 v[16:17], v[16:17], v[34:35] op_sel_hi:[1,0]
	v_pk_mul_f32 v[20:21], v[20:21], v[34:35] op_sel_hi:[1,0]
	v_mul_f32_e32 v41, 0xbfb8aa3b, v19
	v_mul_f32_e32 v34, 0xbfb8aa3b, v33
	v_mul_f32_e32 v35, 0xbfb8aa3b, v25
	v_mul_f32_e32 v36, 0xbfb8aa3b, v29
	v_mul_f32_e32 v37, 0xbfb8aa3b, v27
	v_mul_f32_e32 v38, 0xbfb8aa3b, v31
	v_mul_f32_e32 v39, 0xbfb8aa3b, v17
	v_mul_f32_e32 v40, 0xbfb8aa3b, v21
	v_exp_f32_e32 v41, v41
	v_exp_f32_e32 v34, v34
	v_exp_f32_e32 v35, v35
	v_exp_f32_e32 v36, v36
	v_exp_f32_e32 v37, v37
	v_exp_f32_e32 v38, v38
	v_exp_f32_e32 v39, v39
	v_exp_f32_e32 v40, v40
	v_add_f32_e32 v41, 1.0, v41
	v_add_f32_e32 v34, 1.0, v34
	v_add_f32_e32 v35, 1.0, v35
	v_add_f32_e32 v36, 1.0, v36
	v_add_f32_e32 v37, 1.0, v37
	v_add_f32_e32 v38, 1.0, v38
	v_add_f32_e32 v39, 1.0, v39
	v_add_f32_e32 v40, 1.0, v40
	v_rcp_f32_e32 v41, v41
	v_rcp_f32_e32 v34, v34
	v_rcp_f32_e32 v35, v35
	v_rcp_f32_e32 v36, v36
	v_rcp_f32_e32 v37, v37
	v_rcp_f32_e32 v38, v38
	v_rcp_f32_e32 v39, v39
	v_rcp_f32_e32 v40, v40
	v_mul_f32_e32 v19, v19, v41
	v_mul_f32_e32 v33, v33, v34
	v_mul_f32_e32 v25, v25, v35
	v_mul_f32_e32 v29, v29, v36
	v_mul_f32_e32 v27, v27, v37
	v_mul_f32_e32 v31, v31, v38
	v_mul_f32_e32 v17, v17, v39
	v_mul_f32_e32 v21, v21, v40
	v_mul_f32_e32 v19, v18, v19
	v_mul_f32_e32 v32, v32, v33
	v_mul_f32_e32 v24, v24, v25
	v_mul_f32_e32 v25, v28, v29
	v_mul_f32_e32 v26, v26, v27
	v_mul_f32_e32 v27, v30, v31
	v_mul_f32_e32 v28, v16, v17
	v_mul_f32_e32 v20, v20, v21
	v_cvt_pk_bf16_f32 v16, v32, v24
	v_cvt_pk_bf16_f32 v17, v25, v26
	v_cvt_pk_bf16_f32 v18, v27, v28
	v_cvt_pk_bf16_f32 v19, v20, v19
	global_store_dwordx4 v[22:23], v[16:19], off
	s_nop 0
	s_andn2_b64 vcc, exec, s[0:1]
	v_mov_b32_e32 v17, v8
	v_mov_b32_e32 v8, v13
	v_mov_b32_e32 v13, v10
	v_mov_b32_e32 v10, v15
	v_mov_b32_e32 v15, v0
	v_mov_b32_e32 v0, v5
	v_mov_b32_e32 v5, v2
	v_mov_b32_e32 v2, v7
	v_mov_b32_e32 v16, v12
	v_mov_b32_e32 v12, v14
	v_mov_b32_e32 v14, v4
	v_mov_b32_e32 v4, v6
	v_add_u32_e32 v6, 0xb0, v144
	s_mov_b64 s[0:1], -1
	s_waitcnt vmcnt(7)
	v_fmamk_f32 v7, v234, 0x3a000000, v154
	v_mul_f32_e32 v18, 0x4b800000, v7
	v_cmp_gt_f32_e64 s[4:5], s56, v7
	s_nop 1
	v_cndmask_b32_e64 v7, v7, v18, s[4:5]
	v_rsq_f32_e32 v18, v7
	v_mad_i64_i32 v[6:7], s[30:31], v6, s57, v[120:121]
	v_lshl_add_u64 v[6:7], v[6:7], 0, v[122:123]
	v_mul_f32_e32 v19, 0x45800000, v18
	v_cndmask_b32_e64 v18, v18, v19, s[4:5]
	v_pk_mul_f32 v[2:3], v[2:3], v[18:19] op_sel_hi:[1,0]
	v_pk_mul_f32 v[16:17], v[16:17], v[18:19] op_sel_hi:[1,0]
	v_pk_mul_f32 v[8:9], v[8:9], v[18:19] op_sel_hi:[1,0]
	v_pk_mul_f32 v[12:13], v[12:13], v[18:19] op_sel_hi:[1,0]
	v_pk_mul_f32 v[10:11], v[10:11], v[18:19] op_sel_hi:[1,0]
	v_pk_mul_f32 v[14:15], v[14:15], v[18:19] op_sel_hi:[1,0]
	v_pk_mul_f32 v[0:1], v[0:1], v[18:19] op_sel_hi:[1,0]
	v_pk_mul_f32 v[4:5], v[4:5], v[18:19] op_sel_hi:[1,0]
	v_mul_f32_e32 v25, 0xbfb8aa3b, v3
	v_mul_f32_e32 v18, 0xbfb8aa3b, v17
	v_mul_f32_e32 v19, 0xbfb8aa3b, v9
	v_mul_f32_e32 v20, 0xbfb8aa3b, v13
	v_mul_f32_e32 v21, 0xbfb8aa3b, v11
	v_mul_f32_e32 v22, 0xbfb8aa3b, v15
	v_mul_f32_e32 v23, 0xbfb8aa3b, v1
	v_mul_f32_e32 v24, 0xbfb8aa3b, v5
	v_exp_f32_e32 v25, v25
	v_exp_f32_e32 v18, v18
	v_exp_f32_e32 v19, v19
	v_exp_f32_e32 v20, v20
	v_exp_f32_e32 v21, v21
	v_exp_f32_e32 v22, v22
	v_exp_f32_e32 v23, v23
	v_exp_f32_e32 v24, v24
	v_add_f32_e32 v25, 1.0, v25
	v_add_f32_e32 v18, 1.0, v18
	v_add_f32_e32 v19, 1.0, v19
	v_add_f32_e32 v20, 1.0, v20
	v_add_f32_e32 v21, 1.0, v21
	v_add_f32_e32 v22, 1.0, v22
	v_add_f32_e32 v23, 1.0, v23
	v_add_f32_e32 v24, 1.0, v24
	v_rcp_f32_e32 v25, v25
	v_rcp_f32_e32 v18, v18
	v_rcp_f32_e32 v19, v19
	v_rcp_f32_e32 v20, v20
	v_rcp_f32_e32 v21, v21
	v_rcp_f32_e32 v22, v22
	v_rcp_f32_e32 v23, v23
	v_rcp_f32_e32 v24, v24
	v_mul_f32_e32 v3, v3, v25
	v_mul_f32_e32 v17, v17, v18
	v_mul_f32_e32 v9, v9, v19
	v_mul_f32_e32 v13, v13, v20
	v_mul_f32_e32 v11, v11, v21
	v_mul_f32_e32 v15, v15, v22
	v_mul_f32_e32 v1, v1, v23
	v_mul_f32_e32 v5, v5, v24
	v_mul_f32_e32 v3, v2, v3
	v_mul_f32_e32 v16, v16, v17
	v_mul_f32_e32 v8, v8, v9
	v_mul_f32_e32 v9, v12, v13
	v_mul_f32_e32 v10, v10, v11
	v_mul_f32_e32 v11, v14, v15
	v_mul_f32_e32 v12, v0, v1
	v_mul_f32_e32 v4, v4, v5
	v_cvt_pk_bf16_f32 v0, v16, v8
	v_cvt_pk_bf16_f32 v1, v9, v10
	v_cvt_pk_bf16_f32 v2, v11, v12
	v_cvt_pk_bf16_f32 v3, v4, v3
	global_store_dwordx4 v[6:7], v[0:3], off
	s_cbranch_vccnz .LBB0_701
	s_andn2_b64 vcc, exec, s[8:9]
	s_cbranch_vccnz .LBB0_700
	s_barrier
	s_branch .LBB0_700
